# FoX pre-pass loads hoisted into the unit prologue (data ready when the pre-pass starts)
# speedup vs baseline: 1.0025x; 1.0025x over previous
.LBB0_561:
	s_or_b64 exec, exec, s[40:41]
	v_ashrrev_i32_e32 v19, 6, v165
	v_and_b32_e32 v18, 31, v165
	v_lshlrev_b32_e32 v160, 5, v19
	v_or_b32_e32 v146, v160, v18
	s_lshl_b32 s20, s48, 8
	s_or_b32 s40, s24, s20
	s_mov_b32 s41, s25
	v_ashrrev_i32_e32 v147, 31, v146
	v_lshl_add_u64 v[144:145], s[40:41], 0, v[146:147]
	v_mov_b64_e32 v[12:13], s[22:23]
	v_mad_u64_u32 v[148:149], s[40:41], v144, s70, v[12:13]
	v_bfe_u32 v9, v165, 5, 1
	v_mad_i32_i24 v149, v145, s70, v149
	s_mov_b32 s35, s81
	v_lshl_add_u64 v[14:15], v[148:149], 0, s[34:35]
	v_lshlrev_b32_e32 v190, 4, v9
	v_ashrrev_i32_e32 v152, 3, v165
	v_lshl_add_u64 v[14:15], v[14:15], 0, v[190:191]
	v_ashrrev_i32_e32 v153, 31, v152
	global_load_dwordx4 v[96:99], v[14:15], off offset:3584
	global_load_dwordx4 v[100:103], v[14:15], off offset:3616
	global_load_dwordx4 v[104:107], v[14:15], off offset:3648
	global_load_dwordx4 v[108:111], v[14:15], off offset:3680
	v_lshl_add_u64 v[14:15], s[24:25], 0, v[152:153]
	v_mad_u64_u32 v[12:13], s[40:41], v14, s70, v[12:13]
	v_and_b32_e32 v11, 7, v165
	v_mad_i32_i24 v13, v15, s70, v13
	v_lshlrev_b32_e32 v150, 4, v11
	v_mov_b32_e32 v151, v191
	v_lshl_add_u64 v[12:13], v[12:13], 0, s[34:35]
	v_lshl_add_u64 v[12:13], v[12:13], 0, v[150:151]
	v_add_co_u32_e32 v14, vcc, 0x1000, v12
	v_mov_b32_e32 v11, 0
	s_nop 0
	v_addc_co_u32_e32 v15, vcc, 0, v13, vcc
	v_add_co_u32_e32 v12, vcc, 0x79000, v12
	v_mov_b32_e32 v16, 0
	s_nop 0
	v_addc_co_u32_e32 v13, vcc, 0, v13, vcc
	global_load_dwordx4 v[128:131], v[14:15], off offset:512
	global_load_dwordx4 v[136:139], v[14:15], off offset:1536
	global_load_dwordx4 v[132:135], v[12:13], off offset:512
	global_load_dwordx4 v[140:143], v[12:13], off offset:1536
	v_readfirstlane_b32 s100, v165
	s_nop 3
	s_lshr_b32 s100, s100, 6
	s_lshl_b32 s100, s100, 5
	s_lshl_b32 s101, s48, 8
	s_add_i32 s100, s100, s101
	s_add_i32 s100, s100, -32
	s_mul_i32 s100, s100, 0x1e00
	s_add_u32 s100, s100, 0x7001200
	s_add_u32 s100, s28, s100
	s_addc_u32 s101, s29, 0
	v_and_b32_e32 v60, 31, v165
	v_mul_u32_u24_e32 v60, 0x1e00, v60
	v_bfe_u32 v61, v165, 5, 1
	v_lshl_add_u32 v60, v61, 4, v60
	global_load_dwordx4 v[64:67], v60, s[100:101]
	global_load_dwordx4 v[68:71], v60, s[100:101] offset:32
	global_load_dwordx4 v[72:75], v60, s[100:101] offset:64
	global_load_dwordx4 v[76:79], v60, s[100:101] offset:96
	s_sub_u32 m0, s26, s10
	s_lshr_b32 m0, m0, 14
	s_lshl_b32 m0, m0, 6
	s_lshl_b32 s101, s16, 11
	s_add_i32 m0, m0, s101
	s_getpc_b64 s[100:101]
	s_add_u32 s100, s100, g_ctl@rel32@lo+51204
	s_addc_u32 s101, s101, g_ctl@rel32@hi+51212
	s_add_u32 s100, s100, m0
	s_addc_u32 s101, s101, 0
	v_and_b32_e32 v215, 7, v165
	v_lshlrev_b32_e32 v215, 3, v215
	global_load_dwordx2 v[210:211], v215, s[100:101] sc1
	v_mov_b32_e32 v17, 0
	v_mov_b32_e32 v12, 0
	v_mov_b32_e32 v13, 0
	v_mov_b32_e32 v14, 0
	v_mov_b32_e32 v15, 0
	s_and_saveexec_b64 s[40:41], s[42:43]
	s_cbranch_execz .LBB0_563
	s_waitcnt vmcnt(8)
	v_add_f32_e32 v10, 0, v4
	v_add_f32_e32 v11, v5, v10
	v_add_f32_e32 v16, v6, v11
	v_add_f32_e32 v17, v7, v16
	v_add_f32_e32 v12, v0, v17
	v_add_f32_e32 v13, v1, v12
	v_add_f32_e32 v14, v2, v13
	v_add_f32_e32 v15, v3, v14

.LBB0_574:
	v_readfirstlane_b32 s2, v165
	s_nop 3
	s_lshr_b32 s2, s2, 6
	s_lshl_b32 s2, s2, 5
	s_lshl_b32 s3, s48, 8
	s_add_i32 s2, s2, s3
	s_add_i32 s20, s2, -32
	s_lshl_b32 s42, s20, 2
	v_add_u32_e32 v61, s42, v179
	ds_read_b128 v[32:35], v61
	ds_read_b128 v[36:39], v61 offset:32
	ds_read_b128 v[40:43], v61 offset:64
	ds_read_b128 v[44:47], v61 offset:96
	s_waitcnt lgkmcnt(0)
	v_mfma_f32_32x32x16_bf16 v[32:47], v[64:67], v[96:99], v[32:47]
	v_mfma_f32_32x32x16_bf16 v[32:47], v[68:71], v[100:103], v[32:47]
	v_mfma_f32_32x32x16_bf16 v[32:47], v[72:75], v[104:107], v[32:47]
	v_mfma_f32_32x32x16_bf16 v[32:47], v[76:79], v[108:111], v[32:47]
	s_nop 11
	v_max3_f32 v222, v32, v33, v34
	v_max3_f32 v222, v222, v35, v36
	v_max3_f32 v222, v222, v37, v38
	v_max3_f32 v222, v222, v39, v40
	v_max3_f32 v222, v222, v41, v42
	v_max3_f32 v222, v222, v43, v44
	v_max3_f32 v222, v222, v45, v46
	v_max_f32_e32 v222, v222, v47
	ds_bpermute_b32 v183, v180, v222
	s_waitcnt lgkmcnt(0)
	v_max_f32_e32 v183, v183, v183
	v_max_f32_e32 v182, v222, v183
	v_sub_f32_e32 v182, v182, v161
	v_add_f32_e32 v255, 0xc2200000, v182
	s_mov_b32 s20, 0
